# s5d GLU readout: waves 4-7 start the epilogue a fraction of an n-tile step after waves 0-3 (the two waves of a SIMD no longer expose their bias-load latency at the same time)
# baseline (speedup 1.0000x reference)
; #define LAS __attribute__((address_space(3)))
; template <int NK32>
; __device__ __forceinline__ void wg_gemm256(LAS unsigned char* lds, const hf* W, const int ldw, const h8 (&bf)[NK32], f32x4 (&acc)[16], const int tid, const int fr, const int fq) {
;   constexpr int NS = NK32 / 4; h8 st[8];
; #pragma unroll
;   for (int j = 0; j < 8; ++j) { const int idx = tid + 512 * j; st[j] = *(const h8*)(W + (size_t)(idx >> 4) * ldw + (idx & 15) * 8); }
; #pragma unroll
;   for (int s = 0; s < NS; ++s) {
;     __syncthreads();
; #pragma unroll
;     for (int j = 0; j < 8; ++j) { const int idx = tid + 512 * j; *(LAS h8*)(lds + (idx >> 4) * 272 + (idx & 15) * 16) = st[j]; }
;     if (s + 1 < NS) {
; #pragma unroll
;       for (int j = 0; j < 8; ++j) { const int idx = tid + 512 * j; st[j] = *(const h8*)(W + (size_t)(idx >> 4) * ldw + (s + 1) * 128 + (idx & 15) * 8); } }
;     __syncthreads();
; __device__ __forceinline__ void s5d_wg(const int wvs, const Params& p, LAS unsigned char* lds, int layer, int task) {
;     ...
;   const size_t tok = (size_t)task * 128 + wv * 16 + fr;
;   h8 bf[8]; f32x4 acc[16];
; #pragma unroll
;   for (int i = 0; i < 16; ++i) acc[i] = (f32x4){0.f, 0.f, 0.f, 0.f};
; #pragma unroll
;   for (int ks = 0; ks < 8; ++ks) bf[ks] = *(const h8*)(P + tok * PP + PC_S5 + ks * 32 + fq * 8);
;   wg_gemm256<8>(lds, gluT, 256, bf, acc, tid, fr, fq);
.LBB0_1426:
	s_andn2_b64 vcc, exec, s[4:5]
	s_cbranch_vccnz .LBB0_1428
	s_load_dwordx2 s[4:5], s[6:7], 0xa0
	s_nop 0
	s_load_dwordx2 s[6:7], s[6:7], 0x138
	s_mov_b32 s10, s28
	v_mov_b32_e32 v8, v193
	s_waitcnt lgkmcnt(0)
	s_add_u32 s2, s6, s3
	v_lshlrev_b32_e32 v0, 4, v8
	v_and_b32_e32 v84, 0xf0, v0
	v_add_u32_e32 v0, 0x200, v8
	v_ashrrev_i32_e32 v60, 4, v0
	v_add_u32_e32 v0, 0x400, v8
	s_addc_u32 s9, s7, 0
	v_ashrrev_i32_e32 v62, 4, v0
	v_add_u32_e32 v0, 0x600, v8
	s_add_u32 s8, s2, 0x1900000
	v_ashrrev_i32_e32 v58, 4, v8
	v_ashrrev_i32_e32 v64, 4, v0
	v_add_u32_e32 v0, 0x800, v8
	s_addc_u32 s9, s9, 0
	v_mov_b32_e32 v85, v1
	v_ashrrev_i32_e32 v59, 31, v58
	v_ashrrev_i32_e32 v66, 4, v0
	v_add_u32_e32 v0, 0xa00, v8
	v_lshl_add_u64 v[2:3], s[8:9], 0, v[84:85]
	v_lshlrev_b64 v[86:87], 9, v[58:59]
	v_ashrrev_i32_e32 v61, 31, v60
	v_ashrrev_i32_e32 v63, 31, v62
	v_ashrrev_i32_e32 v68, 4, v0
	v_add_u32_e32 v0, 0xc00, v8
	v_lshl_add_u64 v[4:5], v[2:3], 0, v[86:87]
	v_lshlrev_b64 v[88:89], 9, v[60:61]
	v_lshlrev_b64 v[90:91], 9, v[62:63]
	s_waitcnt vmcnt(4)
	v_ashrrev_i32_e32 v65, 31, v64
	v_ashrrev_i32_e32 v67, 31, v66
	v_ashrrev_i32_e32 v70, 4, v0
	v_add_u32_e32 v0, 0xe00, v8
	v_lshl_add_u64 v[6:7], v[2:3], 0, v[88:89]
	global_load_dwordx4 v[22:25], v[4:5], off
	global_load_dwordx4 v[26:29], v[6:7], off
	v_lshl_add_u64 v[4:5], v[2:3], 0, v[90:91]
	v_lshlrev_b64 v[92:93], 9, v[64:65]
	v_lshlrev_b64 v[94:95], 9, v[66:67]
	v_ashrrev_i32_e32 v69, 31, v68
	v_ashrrev_i32_e32 v71, 31, v70
	v_ashrrev_i32_e32 v72, 4, v0
	v_lshl_add_u64 v[6:7], v[2:3], 0, v[92:93]
	global_load_dwordx4 v[34:37], v[4:5], off
	global_load_dwordx4 v[38:41], v[6:7], off
	v_lshl_add_u64 v[4:5], v[2:3], 0, v[94:95]
	v_lshlrev_b64 v[96:97], 9, v[68:69]
	v_lshlrev_b64 v[98:99], 9, v[70:71]
	v_ashrrev_i32_e32 v73, 31, v72
	v_lshl_add_u64 v[6:7], v[2:3], 0, v[96:97]
	global_load_dwordx4 v[42:45], v[4:5], off
	global_load_dwordx4 v[46:49], v[6:7], off
	v_lshl_add_u64 v[4:5], v[2:3], 0, v[98:99]
	v_lshlrev_b64 v[100:101], 9, v[72:73]
	global_load_dwordx4 v[50:53], v[4:5], off
	v_lshl_add_u64 v[2:3], v[2:3], 0, v[100:101]
	global_load_dwordx4 v[54:57], v[2:3], off
	v_ashrrev_i32_e32 v2, 2, v8
	s_ashr_i32 s11, s10, 31
	v_and_b32_e32 v2, -16, v2
	v_ashrrev_i32_e32 v3, 31, v2
	s_lshl_b64 s[10:11], s[10:11], 7
	v_and_b32_e32 v59, 15, v8
	v_lshl_add_u64 v[110:111], s[10:11], 0, v[2:3]
	v_or_b32_e32 v110, v110, v59
	v_mov_b64_e32 v[2:3], s[6:7]
	v_mad_u64_u32 v[2:3], s[10:11], v110, s51, v[2:3]
	v_bfe_u32 v0, v8, 4, 2
	v_mad_i32_i24 v3, v111, s51, v3
	s_mov_b64 s[10:11], 0x4d0c000
	v_lshl_add_u64 v[78:79], v[2:3], 0, s[10:11]
	v_lshlrev_b32_e32 v106, 4, v0
	v_mov_b32_e32 v107, v1
	v_lshl_add_u64 v[2:3], v[78:79], 0, v[106:107]
	global_load_dwordx4 v[74:77], v[2:3], off
	global_load_dwordx4 v[80:83], v[2:3], off offset:64
	global_load_dwordx4 v[30:33], v[2:3], off offset:128
	global_load_dwordx4 v[14:17], v[2:3], off offset:192
	global_load_dwordx4 v[18:21], v[2:3], off offset:256
	global_load_dwordx4 v[10:13], v[2:3], off offset:320
	global_load_dwordx4 v[6:9], v[2:3], off offset:384
	s_nop 0
	global_load_dwordx4 v[2:5], v[2:3], off offset:448
	v_add_u32_e32 v102, 0, v84
	v_mul_u32_u24_e32 v59, 0x110, v59
	v_add3_u32 v107, 0, v106, v59
	v_mad_u64_u32 v[58:59], s[10:11], v58, s67, v[102:103]
	v_mad_u64_u32 v[60:61], s[10:11], v60, s67, v[102:103]
	v_mad_u64_u32 v[62:63], s[10:11], v62, s67, v[102:103]
	v_mad_u64_u32 v[64:65], s[10:11], v64, s67, v[102:103]
	v_mad_u64_u32 v[66:67], s[10:11], v66, s67, v[102:103]
	v_mad_u64_u32 v[68:69], s[10:11], v68, s67, v[102:103]
	v_mad_u64_u32 v[70:71], s[10:11], v70, s67, v[102:103]
	s_barrier
	v_mad_u64_u32 v[72:73], s[10:11], v72, s67, v[102:103]
	v_readlane_b32 s2, v254, 9
	s_lshl_b32 s30, s2, 8
	v_lshlrev_b32_e32 v0, 3, v0
	v_lshl_add_u64 v[108:109], v[78:79], 0, v[0:1]
	s_mov_b32 s2, s31
	s_waitcnt vmcnt(15)
	ds_write_b128 v58, v[22:25]
	s_waitcnt vmcnt(14)
	ds_write_b128 v60, v[26:29]
	v_lshl_add_u64 v[22:23], s[8:9], 0, v[86:87]
	v_lshl_add_u64 v[24:25], s[8:9], 0, v[88:89]
	v_lshl_add_u64 v[22:23], v[22:23], 0, v[84:85]
	v_lshl_add_u64 v[24:25], v[24:25], 0, v[84:85]
	s_waitcnt vmcnt(13)
	ds_write_b128 v62, v[34:37]
	s_waitcnt vmcnt(12)
	ds_write_b128 v64, v[38:41]
	v_lshl_add_u64 v[34:35], s[8:9], 0, v[90:91]
	v_lshl_add_u64 v[36:37], s[8:9], 0, v[92:93]
	v_lshl_add_u64 v[34:35], v[34:35], 0, v[84:85]
	v_lshl_add_u64 v[38:39], v[36:37], 0, v[84:85]
	s_waitcnt vmcnt(11)
	ds_write_b128 v66, v[42:45]
	s_waitcnt vmcnt(10)
	ds_write_b128 v68, v[46:49]
	v_lshl_add_u64 v[42:43], s[8:9], 0, v[94:95]
	v_lshl_add_u64 v[44:45], s[8:9], 0, v[96:97]
	s_waitcnt vmcnt(9)
	ds_write_b128 v70, v[50:53]
	v_lshl_add_u64 v[50:51], s[8:9], 0, v[98:99]
	v_lshl_add_u64 v[52:53], s[8:9], 0, v[100:101]
	s_waitcnt vmcnt(8)
	ds_write_b128 v72, v[54:57]
	v_lshl_add_u64 v[42:43], v[42:43], 0, v[84:85]
	v_lshl_add_u64 v[46:47], v[44:45], 0, v[84:85]
	v_lshl_add_u64 v[50:51], v[50:51], 0, v[84:85]
	v_lshl_add_u64 v[52:53], v[52:53], 0, v[84:85]
	global_load_dwordx4 v[26:29], v[22:23], off offset:256
	s_nop 0
	global_load_dwordx4 v[22:25], v[24:25], off offset:256
	s_nop 0
	global_load_dwordx4 v[34:37], v[34:35], off offset:256
	s_nop 0
	global_load_dwordx4 v[38:41], v[38:39], off offset:256
	s_nop 0
	global_load_dwordx4 v[42:45], v[42:43], off offset:256
	s_nop 0
	global_load_dwordx4 v[46:49], v[46:47], off offset:256
	s_nop 0
	global_load_dwordx4 v[54:57], v[50:51], off offset:256
	s_nop 0
	global_load_dwordx4 v[50:53], v[52:53], off offset:256
	s_waitcnt lgkmcnt(0)
	s_barrier
; #define LAS __attribute__((address_space(3)))
; __device__ __forceinline__ f32x4 mfma16(h8 a, h8 b, f32x4 c) { return __builtin_amdgcn_mfma_f32_16x16x32_f16(a, b, c, 0, 0, 0); }
; template <int NK32>
; __device__ __forceinline__ void wg_gemm256(LAS unsigned char* lds, const hf* W, const int ldw, const h8 (&bf)[NK32], f32x4 (&acc)[16], const int tid, const int fr, const int fq) {
;     ...
; #pragma unroll
;     for (int ks = 0; ks < 4; ++ks)
; #pragma unroll
;       for (int nt = 0; nt < 16; ++nt) acc[nt] = mfma16(*(const LAS h8*)(lds + (nt * 16 + fr) * 272 + ks * 64 + fq * 16), bf[s * 4 + ks], acc[nt]);
; __device__ __forceinline__ void s5d_wg(const int wvs, const Params& p, LAS unsigned char* lds, int layer, int task) {
;     ...
;   const float* gb = p.in[I_GLUB] + layer * 256;
	ds_read_b128 v[84:87], v107
	ds_read_b128 v[88:91], v107 offset:64
	ds_read_b128 v[92:95], v107 offset:4352
	ds_read_b128 v[96:99], v107 offset:4416
	ds_read_b128 v[100:103], v107 offset:8704
	ds_read_b128 v[112:115], v107 offset:8768
	ds_read_b128 v[116:119], v107 offset:13056
	ds_read_b128 v[120:123], v107 offset:13120
	ds_read_b128 v[124:127], v107 offset:17408
	ds_read_b128 v[128:131], v107 offset:17472
	ds_read_b128 v[132:135], v107 offset:21760
	ds_read_b128 v[136:139], v107 offset:21824
	ds_read_b128 v[140:143], v107 offset:26112
	ds_read_b128 v[144:147], v107 offset:26176
	ds_read_b128 v[148:151], v107 offset:30464
	ds_read_b128 v[152:155], v107 offset:30528
	ds_read_b128 v[156:159], v107 offset:34816
	ds_read_b128 v[160:163], v107 offset:34880
	ds_read_b128 v[164:167], v107 offset:39168
	ds_read_b128 v[168:171], v107 offset:39232
	ds_read_b128 v[172:175], v107 offset:43520
	ds_read_b128 v[176:179], v107 offset:43584
	ds_read_b128 v[180:183], v107 offset:47872
	ds_read_b128 v[184:187], v107 offset:47936
	ds_read_b128 v[188:191], v107 offset:52224
	ds_read_b128 v[194:197], v107 offset:52288
	ds_read_b128 v[224:227], v107 offset:56576
	ds_read_b128 v[228:231], v107 offset:56640
	ds_read_b128 v[232:235], v107 offset:60928
	ds_read_b128 v[236:239], v107 offset:60992
	ds_read_b128 v[240:243], v107 offset:65280
	ds_read_b128 v[244:247], v107 offset:65344
	s_waitcnt vmcnt(15) lgkmcnt(14)
	v_mfma_f32_16x16x32_f16 v[84:87], v[84:87], v[74:77], 0
	s_lshl_b64 s[8:9], s[30:31], 2
	s_add_u32 s4, s4, s8
	s_addc_u32 s5, s5, s9
	v_mfma_f32_16x16x32_f16 v[92:95], v[92:95], v[74:77], 0
	v_mfma_f32_16x16x32_f16 v[100:103], v[100:103], v[74:77], 0
	v_mfma_f32_16x16x32_f16 v[116:119], v[116:119], v[74:77], 0
	v_mfma_f32_16x16x32_f16 v[124:127], v[124:127], v[74:77], 0
	v_mfma_f32_16x16x32_f16 v[132:135], v[132:135], v[74:77], 0
	v_mfma_f32_16x16x32_f16 v[140:143], v[140:143], v[74:77], 0
	v_mfma_f32_16x16x32_f16 v[148:151], v[148:151], v[74:77], 0
	v_mfma_f32_16x16x32_f16 v[156:159], v[156:159], v[74:77], 0
	s_waitcnt lgkmcnt(13)
	v_mfma_f32_16x16x32_f16 v[164:167], v[164:167], v[74:77], 0
	s_waitcnt lgkmcnt(11)
	v_mfma_f32_16x16x32_f16 v[172:175], v[172:175], v[74:77], 0
	s_waitcnt lgkmcnt(9)
	v_mfma_f32_16x16x32_f16 v[180:183], v[180:183], v[74:77], 0
	s_waitcnt lgkmcnt(7)
	v_mfma_f32_16x16x32_f16 v[188:191], v[188:191], v[74:77], 0
	s_waitcnt lgkmcnt(5)
	v_mfma_f32_16x16x32_f16 v[224:227], v[224:227], v[74:77], 0
	s_waitcnt lgkmcnt(3)
	v_mfma_f32_16x16x32_f16 v[232:235], v[232:235], v[74:77], 0
	s_waitcnt lgkmcnt(1)
	v_mfma_f32_16x16x32_f16 v[74:77], v[240:243], v[74:77], 0
	s_waitcnt vmcnt(14)
	v_mfma_f32_16x16x32_f16 v[84:87], v[88:91], v[80:83], v[84:87]
	v_mfma_f32_16x16x32_f16 v[88:91], v[96:99], v[80:83], v[92:95]
	v_mfma_f32_16x16x32_f16 v[92:95], v[112:115], v[80:83], v[100:103]
	v_mfma_f32_16x16x32_f16 v[96:99], v[120:123], v[80:83], v[116:119]
	v_mfma_f32_16x16x32_f16 v[100:103], v[128:131], v[80:83], v[124:127]
	v_mfma_f32_16x16x32_f16 v[112:115], v[136:139], v[80:83], v[132:135]
	v_mfma_f32_16x16x32_f16 v[116:119], v[144:147], v[80:83], v[140:143]
	v_mfma_f32_16x16x32_f16 v[120:123], v[152:155], v[80:83], v[148:151]
	v_mfma_f32_16x16x32_f16 v[124:127], v[160:163], v[80:83], v[156:159]
	v_mfma_f32_16x16x32_f16 v[128:131], v[168:171], v[80:83], v[164:167]
	v_mfma_f32_16x16x32_f16 v[132:135], v[176:179], v[80:83], v[172:175]
	v_mfma_f32_16x16x32_f16 v[136:139], v[184:187], v[80:83], v[180:183]
	v_mfma_f32_16x16x32_f16 v[140:143], v[194:197], v[80:83], v[188:191]
	v_mfma_f32_16x16x32_f16 v[144:147], v[228:231], v[80:83], v[224:227]
	v_mfma_f32_16x16x32_f16 v[148:151], v[236:239], v[80:83], v[232:235]
	s_waitcnt lgkmcnt(0)
	v_mfma_f32_16x16x32_f16 v[74:77], v[244:247], v[80:83], v[74:77]
	ds_read_b128 v[80:83], v107 offset:128
	ds_read_b128 v[152:155], v107 offset:192
	s_waitcnt vmcnt(13) lgkmcnt(1)
	v_mfma_f32_16x16x32_f16 v[80:83], v[80:83], v[30:33], v[84:87]
	s_nop 2
	ds_read_b128 v[84:87], v107 offset:4480
	ds_read_b128 v[156:159], v107 offset:4544
	s_waitcnt lgkmcnt(1)
	v_mfma_f32_16x16x32_f16 v[84:87], v[84:87], v[30:33], v[88:91]
	s_nop 2
	ds_read_b128 v[88:91], v107 offset:8832
	ds_read_b128 v[160:163], v107 offset:8896
	s_waitcnt lgkmcnt(1)
	v_mfma_f32_16x16x32_f16 v[88:91], v[88:91], v[30:33], v[92:95]
	s_nop 2
	ds_read_b128 v[92:95], v107 offset:13184
	ds_read_b128 v[164:167], v107 offset:13248
	s_waitcnt lgkmcnt(1)
	v_mfma_f32_16x16x32_f16 v[92:95], v[92:95], v[30:33], v[96:99]
	s_nop 2
	ds_read_b128 v[96:99], v107 offset:17536
	ds_read_b128 v[168:171], v107 offset:17600
	s_waitcnt lgkmcnt(1)
	v_mfma_f32_16x16x32_f16 v[96:99], v[96:99], v[30:33], v[100:103]
	s_nop 2
	ds_read_b128 v[100:103], v107 offset:21888
	ds_read_b128 v[172:175], v107 offset:21952
	s_waitcnt lgkmcnt(1)
	v_mfma_f32_16x16x32_f16 v[100:103], v[100:103], v[30:33], v[112:115]
	s_nop 2
	ds_read_b128 v[112:115], v107 offset:26240
	ds_read_b128 v[176:179], v107 offset:26304
	s_waitcnt lgkmcnt(1)
	v_mfma_f32_16x16x32_f16 v[112:115], v[112:115], v[30:33], v[116:119]
	s_nop 2
	ds_read_b128 v[116:119], v107 offset:30592
	ds_read_b128 v[180:183], v107 offset:30656
	s_waitcnt lgkmcnt(1)
	v_mfma_f32_16x16x32_f16 v[116:119], v[116:119], v[30:33], v[120:123]
	s_nop 2
	ds_read_b128 v[120:123], v107 offset:34944
	ds_read_b128 v[184:187], v107 offset:35008
	s_waitcnt lgkmcnt(1)
	v_mfma_f32_16x16x32_f16 v[120:123], v[120:123], v[30:33], v[124:127]
	s_nop 2
	ds_read_b128 v[124:127], v107 offset:39296
	ds_read_b128 v[188:191], v107 offset:39360
	s_waitcnt lgkmcnt(1)
	v_mfma_f32_16x16x32_f16 v[124:127], v[124:127], v[30:33], v[128:131]
	s_nop 2
	ds_read_b128 v[128:131], v107 offset:43648
	ds_read_b128 v[194:197], v107 offset:43712
	s_waitcnt lgkmcnt(1)
	v_mfma_f32_16x16x32_f16 v[128:131], v[128:131], v[30:33], v[132:135]
	s_nop 2
	ds_read_b128 v[132:135], v107 offset:48000
	ds_read_b128 v[224:227], v107 offset:48064
	s_waitcnt lgkmcnt(1)
	v_mfma_f32_16x16x32_f16 v[132:135], v[132:135], v[30:33], v[136:139]
	s_nop 2
	ds_read_b128 v[136:139], v107 offset:52352
	ds_read_b128 v[228:231], v107 offset:52416
	s_waitcnt lgkmcnt(1)
	v_mfma_f32_16x16x32_f16 v[136:139], v[136:139], v[30:33], v[140:143]
	s_nop 2
	ds_read_b128 v[140:143], v107 offset:56704
	ds_read_b128 v[232:235], v107 offset:56768
	s_waitcnt lgkmcnt(1)
	v_mfma_f32_16x16x32_f16 v[140:143], v[140:143], v[30:33], v[144:147]
	s_nop 2
	ds_read_b128 v[144:147], v107 offset:61056
	ds_read_b128 v[236:239], v107 offset:61120
	s_waitcnt lgkmcnt(1)
	v_mfma_f32_16x16x32_f16 v[144:147], v[144:147], v[30:33], v[148:151]
	s_nop 2
	ds_read_b128 v[148:151], v107 offset:65408
	ds_read_b128 v[240:243], v107 offset:65472
	s_waitcnt lgkmcnt(0)
	s_barrier
; #define LAS __attribute__((address_space(3)))
; __device__ __forceinline__ float sigmoidf_(float x) { return __builtin_amdgcn_rcpf(1.0f + __expf(-x)); }
; __device__ __forceinline__ f32x4 mfma16(h8 a, h8 b, f32x4 c) { return __builtin_amdgcn_mfma_f32_16x16x32_f16(a, b, c, 0, 0, 0); }
; template <int NK32>
; __device__ __forceinline__ void wg_gemm256(LAS unsigned char* lds, const hf* W, const int ldw, const h8 (&bf)[NK32], f32x4 (&acc)[16], const int tid, const int fr, const int fq) {
;     ...
;   for (int s = 0; s < NS; ++s) {
;     __syncthreads();
; #pragma unroll
;     for (int j = 0; j < 8; ++j) { const int idx = tid + 512 * j; *(LAS h8*)(lds + (idx >> 4) * 272 + (idx & 15) * 16) = st[j]; }
;     if (s + 1 < NS) {
; #pragma unroll
;       for (int j = 0; j < 8; ++j) { const int idx = tid + 512 * j; st[j] = *(const h8*)(W + (size_t)(idx >> 4) * ldw + (s + 1) * 128 + (idx & 15) * 8); } }
;     __syncthreads();
; #pragma unroll
;     for (int ks = 0; ks < 4; ++ks)
; #pragma unroll
;       for (int nt = 0; nt < 16; ++nt) acc[nt] = mfma16(*(const LAS h8*)(lds + (nt * 16 + fr) * 272 + ks * 64 + fq * 16), bf[s * 4 + ks], acc[nt]);
; __device__ __forceinline__ void s5d_wg(const int wvs, const Params& p, LAS unsigned char* lds, int layer, int task) {
;     ...
; #pragma unroll
;   for (int nt = 0; nt < 16; ++nt) { const int n4 = nt * 16 + fq * 4; const h4 zz = *(const h4*)(P + tok * PP + PC_S5 + n4); const f32x4 b4 = *(const f32x4*)(gb + n4); h4 o;
; #pragma unroll
;     for (int r = 0; r < 4; ++r) o[r] = (hf)((float)zz[r] * sigmoidf_(acc[nt][r] + b4[r]));
;     *(h4*)(Y + tok * DM + n4) = o; }
	v_mfma_f32_16x16x32_f16 v[30:33], v[148:151], v[30:33], v[74:77]
	s_waitcnt vmcnt(7)
	ds_write_b128 v58, v[26:29]
	s_waitcnt vmcnt(6)
	ds_write_b128 v60, v[22:25]
	s_waitcnt vmcnt(5)
	ds_write_b128 v62, v[34:37]
	s_waitcnt vmcnt(4)
	ds_write_b128 v64, v[38:41]
	s_waitcnt vmcnt(3)
	ds_write_b128 v66, v[42:45]
	s_waitcnt vmcnt(2)
	ds_write_b128 v68, v[46:49]
	s_waitcnt vmcnt(1)
	ds_write_b128 v70, v[54:57]
	s_waitcnt vmcnt(0)
	ds_write_b128 v72, v[50:53]
	s_waitcnt lgkmcnt(0)
	v_mfma_f32_16x16x32_f16 v[74:77], v[152:155], v[14:17], v[80:83]
	s_barrier
	v_readfirstlane_b32 vcc_lo, v193
	s_nop 0
	s_cmp_lt_u32 vcc_lo, 0x100
	s_cbranch_scc1 .Ls5d_go
	s_sleep 12
.Ls5d_go:
	v_mfma_f32_16x16x32_f16 v[80:83], v[156:159], v[14:17], v[84:87]
	v_mfma_f32_16x16x32_f16 v[84:87], v[160:163], v[14:17], v[88:91]
	v_mfma_f32_16x16x32_f16 v[88:91], v[164:167], v[14:17], v[92:95]
	v_mfma_f32_16x16x32_f16 v[92:95], v[168:171], v[14:17], v[96:99]
	v_mfma_f32_16x16x32_f16 v[96:99], v[172:175], v[14:17], v[100:103]
	v_mfma_f32_16x16x32_f16 v[100:103], v[176:179], v[14:17], v[112:115]
	v_mfma_f32_16x16x32_f16 v[112:115], v[180:183], v[14:17], v[116:119]
	v_mfma_f32_16x16x32_f16 v[116:119], v[184:187], v[14:17], v[120:123]
	v_mfma_f32_16x16x32_f16 v[120:123], v[188:191], v[14:17], v[124:127]
	v_mfma_f32_16x16x32_f16 v[124:127], v[194:197], v[14:17], v[128:131]
	v_mfma_f32_16x16x32_f16 v[128:131], v[224:227], v[14:17], v[132:135]
	v_mfma_f32_16x16x32_f16 v[132:135], v[228:231], v[14:17], v[136:139]
	v_mfma_f32_16x16x32_f16 v[136:139], v[232:235], v[14:17], v[140:143]
	v_mfma_f32_16x16x32_f16 v[140:143], v[236:239], v[14:17], v[144:147]
	v_mfma_f32_16x16x32_f16 v[144:147], v[240:243], v[14:17], v[30:33]
	ds_read_b128 v[14:17], v107
	ds_read_b128 v[148:151], v107 offset:64
	s_waitcnt lgkmcnt(1)
	v_mfma_f32_16x16x32_f16 v[152:155], v[14:17], v[18:21], v[74:77]
	ds_read_b128 v[14:17], v107 offset:4352
	ds_read_b128 v[156:159], v107 offset:4416
	s_waitcnt lgkmcnt(1)
	v_mfma_f32_16x16x32_f16 v[80:83], v[14:17], v[18:21], v[80:83]
	ds_read_b128 v[14:17], v107 offset:8704
	ds_read_b128 v[160:163], v107 offset:8768
	s_waitcnt lgkmcnt(1)
	v_mfma_f32_16x16x32_f16 v[164:167], v[14:17], v[18:21], v[84:87]
	ds_read_b128 v[14:17], v107 offset:13056
	ds_read_b128 v[168:171], v107 offset:13120
	s_waitcnt lgkmcnt(1)
	v_mfma_f32_16x16x32_f16 v[172:175], v[14:17], v[18:21], v[88:91]
	ds_read_b128 v[14:17], v107 offset:17408
	ds_read_b128 v[176:179], v107 offset:17472
	s_waitcnt lgkmcnt(1)
	v_mfma_f32_16x16x32_f16 v[180:183], v[14:17], v[18:21], v[92:95]
	ds_read_b128 v[14:17], v107 offset:21760
	ds_read_b128 v[184:187], v107 offset:21824
	s_waitcnt lgkmcnt(1)
	v_mfma_f32_16x16x32_f16 v[188:191], v[14:17], v[18:21], v[96:99]
	ds_read_b128 v[14:17], v107 offset:26112
	ds_read_b128 v[194:197], v107 offset:26176
	s_waitcnt lgkmcnt(1)
	v_mfma_f32_16x16x32_f16 v[224:227], v[14:17], v[18:21], v[100:103]
	ds_read_b128 v[14:17], v107 offset:30464
	ds_read_b128 v[86:89], v107 offset:30528
	s_waitcnt lgkmcnt(1)
	v_mfma_f32_16x16x32_f16 v[90:93], v[14:17], v[18:21], v[112:115]
	ds_read_b128 v[14:17], v107 offset:34816
	ds_read_b128 v[70:73], v107 offset:34880
	s_waitcnt lgkmcnt(1)
	v_mfma_f32_16x16x32_f16 v[74:77], v[14:17], v[18:21], v[116:119]
	ds_read_b128 v[14:17], v107 offset:39168
	ds_read_b128 v[62:65], v107 offset:39232
	s_waitcnt lgkmcnt(1)
	v_mfma_f32_16x16x32_f16 v[66:69], v[14:17], v[18:21], v[120:123]
	ds_read_b128 v[14:17], v107 offset:43520
	ds_read_b128 v[54:57], v107 offset:43584
	s_waitcnt lgkmcnt(1)
	v_mfma_f32_16x16x32_f16 v[58:61], v[14:17], v[18:21], v[124:127]
	ds_read_b128 v[14:17], v107 offset:47872
	ds_read_b128 v[46:49], v107 offset:47936
	s_waitcnt lgkmcnt(1)
	v_mfma_f32_16x16x32_f16 v[50:53], v[14:17], v[18:21], v[128:131]
	ds_read_b128 v[14:17], v107 offset:52224
	ds_read_b128 v[38:41], v107 offset:52288
	s_waitcnt lgkmcnt(1)
	v_mfma_f32_16x16x32_f16 v[42:45], v[14:17], v[18:21], v[132:135]
	ds_read_b128 v[14:17], v107 offset:56576
	ds_read_b128 v[30:33], v107 offset:56640
	s_waitcnt lgkmcnt(1)
	v_mfma_f32_16x16x32_f16 v[34:37], v[14:17], v[18:21], v[136:139]
	ds_read_b128 v[14:17], v107 offset:60928
	ds_read_b128 v[22:25], v107 offset:60992
	s_waitcnt lgkmcnt(1)
	v_mfma_f32_16x16x32_f16 v[26:29], v[14:17], v[18:21], v[140:143]
	ds_read_b128 v[94:97], v107 offset:65280
	ds_read_b128 v[14:17], v107 offset:65344
	global_load_dwordx4 v[120:123], v106, s[4:5]
	global_load_dwordx2 v[132:133], v[108:109], off
	ds_read_b128 v[124:127], v107 offset:128
	ds_read_b128 v[128:131], v107 offset:192
	v_mfma_f32_16x16x32_f16 v[112:115], v[148:151], v[10:13], v[152:155]
	s_waitcnt lgkmcnt(1)
	v_mfma_f32_16x16x32_f16 v[112:115], v[124:127], v[6:9], v[112:115]
	s_waitcnt lgkmcnt(0)
	v_mfma_f32_16x16x32_f16 v[112:115], v[128:131], v[2:5], v[112:115]
	ds_read_b128 v[124:127], v107 offset:4480
	ds_read_b128 v[128:131], v107 offset:4544
	v_mfma_f32_16x16x32_f16 v[116:119], v[156:159], v[10:13], v[80:83]
	s_waitcnt vmcnt(1)
	s_nop 3
	v_add_f32_e32 v112, v112, v120
	v_mul_f32_e32 v112, 0xbfb8aa3b, v112
	v_exp_f32_e32 v120, v112
	v_add_f32_e32 v112, v113, v121
	v_add_f32_e32 v114, v114, v122
	v_add_f32_e32 v115, v115, v123
	v_mul_f32_e32 v112, 0xbfb8aa3b, v112
	v_mul_f32_e32 v114, 0xbfb8aa3b, v114
	v_mul_f32_e32 v115, 0xbfb8aa3b, v115
	v_exp_f32_e32 v121, v112
	v_exp_f32_e32 v114, v114
	v_exp_f32_e32 v115, v115
	v_lshlrev_b64 v[112:113], 11, v[110:111]
	v_add_f32_e32 v110, 1.0, v120
	v_rcp_f32_e32 v120, v110
	v_add_f32_e32 v110, 1.0, v121
	v_add_f32_e32 v114, 1.0, v114
	v_add_f32_e32 v115, 1.0, v115
	s_waitcnt lgkmcnt(1)
	v_mfma_f32_16x16x32_f16 v[116:119], v[124:127], v[6:9], v[116:119]
	v_rcp_f32_e32 v121, v110
	s_waitcnt vmcnt(0)
; __device__ __forceinline__ float sigmoidf_(float x) { return __builtin_amdgcn_rcpf(1.0f + __expf(-x)); }
; __device__ __forceinline__ void s5d_wg(const int wvs, const Params& p, LAS unsigned char* lds, int layer, int task) {
;     ...
; #pragma unroll
;   for (int nt = 0; nt < 16; ++nt) { const int n4 = nt * 16 + fq * 4; const h4 zz = *(const h4*)(P + tok * PP + PC_S5 + n4); const f32x4 b4 = *(const f32x4*)(gb + n4); h4 o;
; #pragma unroll
;     for (int r = 0; r < 4; ++r) o[r] = (hf)((float)zz[r] * sigmoidf_(acc[nt][r] + b4[r]));
;     *(h4*)(Y + tok * DM + n4) = o; }
	v_cvt_f32_f16_e32 v124, v132
	v_cvt_f32_f16_sdwa v125, v132 dst_sel:DWORD dst_unused:UNUSED_PAD src0_sel:WORD_1
	v_rcp_f32_e32 v114, v114
	v_rcp_f32_e32 v115, v115
	v_cvt_f32_f16_e32 v122, v133
	v_cvt_f32_f16_sdwa v123, v133 dst_sel:DWORD dst_unused:UNUSED_PAD src0_sel:WORD_1
	v_lshl_add_u64 v[112:113], s[6:7], 0, v[112:113]
	v_lshl_add_u64 v[132:133], v[112:113], 0, v[0:1]
	v_pk_mul_f32 v[120:121], v[120:121], v[124:125]
	v_pk_mul_f32 v[114:115], v[114:115], v[122:123]
	v_add_co_u32_e32 v112, vcc, s73, v132
	v_cvt_pk_f16_f32 v120, v120, v121
	v_cvt_pk_f16_f32 v121, v114, v115
	v_addc_co_u32_e32 v113, vcc, 0, v133, vcc
	global_load_dwordx2 v[134:135], v[108:109], off offset:32
	global_load_dwordx2 v[136:137], v[108:109], off offset:64
	global_load_dwordx2 v[110:111], v[108:109], off offset:96
	s_waitcnt lgkmcnt(0)
	v_mfma_f32_16x16x32_f16 v[116:119], v[128:131], v[2:5], v[116:119]
	global_store_dwordx2 v[112:113], v[120:121], off
	global_load_dwordx4 v[112:115], v106, s[4:5] offset:64
	ds_read_b128 v[120:123], v107 offset:8832
	ds_read_b128 v[124:127], v107 offset:8896
	v_mfma_f32_16x16x32_f16 v[98:101], v[160:163], v[10:13], v[164:167]
	s_mov_b64 s[6:7], 0x2b0c000
	s_waitcnt vmcnt(0)
	s_nop 0
	v_add_f32_e32 v0, v116, v112
	v_mul_f32_e32 v0, 0xbfb8aa3b, v0
	v_add_f32_e32 v112, v117, v113
	v_exp_f32_e32 v0, v0
	v_mul_f32_e32 v112, 0xbfb8aa3b, v112
	v_exp_f32_e32 v112, v112
	s_waitcnt lgkmcnt(1)
	v_mfma_f32_16x16x32_f16 v[120:123], v[120:123], v[6:9], v[98:101]
	v_add_f32_e32 v0, 1.0, v0
	v_cvt_f32_f16_sdwa v113, v134 dst_sel:DWORD dst_unused:UNUSED_PAD src0_sel:WORD_1
	v_cvt_f32_f16_e32 v116, v135
	v_rcp_f32_e32 v100, v0
	v_add_f32_e32 v0, 1.0, v112
	v_rcp_f32_e32 v101, v0
	v_add_f32_e32 v0, v118, v114
	v_mul_f32_e32 v0, 0xbfb8aa3b, v0
	v_add_f32_e32 v98, v119, v115
	v_exp_f32_e32 v0, v0
	v_mul_f32_e32 v98, 0xbfb8aa3b, v98
	v_exp_f32_e32 v98, v98
	v_cvt_f32_f16_e32 v112, v134
	v_add_f32_e32 v0, 1.0, v0
	v_rcp_f32_e32 v114, v0
	v_add_f32_e32 v0, 1.0, v98
	v_rcp_f32_e32 v115, v0
	v_cvt_f32_f16_sdwa v117, v135 dst_sel:DWORD dst_unused:UNUSED_PAD src0_sel:WORD_1
	v_pk_mul_f32 v[100:101], v[100:101], v[112:113]
	v_lshl_add_u64 v[98:99], v[132:133], 0, s[6:7]
	v_cvt_pk_f16_f32 v100, v100, v101
	v_pk_mul_f32 v[112:113], v[114:115], v[116:117]
	s_waitcnt lgkmcnt(0)
	v_mfma_f32_16x16x32_f16 v[116:119], v[124:127], v[2:5], v[120:123]
	v_cvt_pk_f16_f32 v101, v112, v113
	global_store_dwordx2 v[98:99], v[100:101], off offset:32
	global_load_dwordx4 v[112:115], v106, s[4:5] offset:128
	v_mfma_f32_16x16x32_f16 v[102:105], v[168:171], v[10:13], v[172:175]
	ds_read_b128 v[120:123], v107 offset:13184
	ds_read_b128 v[124:127], v107 offset:13248
	s_waitcnt vmcnt(0)
	s_nop 0
	v_add_f32_e32 v0, v116, v112
	v_mul_f32_e32 v0, 0xbfb8aa3b, v0
	v_add_f32_e32 v100, v117, v113
	v_exp_f32_e32 v0, v0
	v_mul_f32_e32 v100, 0xbfb8aa3b, v100
	v_exp_f32_e32 v100, v100
	v_cvt_f32_f16_e32 v116, v136
	v_add_f32_e32 v0, 1.0, v0
	v_rcp_f32_e32 v112, v0
	v_add_f32_e32 v0, 1.0, v100
	v_rcp_f32_e32 v113, v0
	v_add_f32_e32 v0, v118, v114
	v_mul_f32_e32 v0, 0xbfb8aa3b, v0
	v_add_f32_e32 v100, v119, v115
	v_exp_f32_e32 v0, v0
	v_mul_f32_e32 v100, 0xbfb8aa3b, v100
	v_exp_f32_e32 v100, v100
	v_cvt_f32_f16_sdwa v117, v136 dst_sel:DWORD dst_unused:UNUSED_PAD src0_sel:WORD_1
	v_add_f32_e32 v0, 1.0, v0
	v_rcp_f32_e32 v114, v0
	v_add_f32_e32 v0, 1.0, v100
	v_rcp_f32_e32 v115, v0
	v_cvt_f32_f16_e32 v118, v137
	v_cvt_f32_f16_sdwa v119, v137 dst_sel:DWORD dst_unused:UNUSED_PAD src0_sel:WORD_1
	s_waitcnt lgkmcnt(1)
	v_mfma_f32_16x16x32_f16 v[100:103], v[120:123], v[6:9], v[102:105]
	s_nop 2
	v_mul_f32_e64 v104, v112, v116
	v_mul_f32_e64 v105, v113, v117
	v_pk_mul_f32 v[112:113], v[114:115], v[118:119]
	v_cvt_pk_f16_f32 v104, v104, v105
	v_cvt_pk_f16_f32 v105, v112, v113
	global_store_dwordx2 v[98:99], v[104:105], off offset:64
	global_load_dwordx4 v[112:115], v106, s[4:5] offset:192
	s_waitcnt lgkmcnt(0)
	v_mfma_f32_16x16x32_f16 v[100:103], v[124:127], v[2:5], v[100:103]
	global_load_dwordx2 v[104:105], v[108:109], off offset:128
	v_mfma_f32_16x16x32_f16 v[86:89], v[86:89], v[10:13], v[90:93]
	s_nop 2
	v_cvt_f32_f16_e32 v92, v110
	v_mfma_f32_16x16x32_f16 v[70:73], v[70:73], v[10:13], v[74:77]
	s_waitcnt vmcnt(1)
	v_add_f32_e32 v0, v100, v112
	v_mul_f32_e32 v0, 0xbfb8aa3b, v0
	v_add_f32_e32 v100, v101, v113
	v_exp_f32_e32 v0, v0
	v_mul_f32_e32 v100, 0xbfb8aa3b, v100
	v_exp_f32_e32 v100, v100
	v_add_f32_e32 v93, v103, v115
	v_add_f32_e32 v0, 1.0, v0
	v_rcp_f32_e32 v90, v0
	v_add_f32_e32 v0, 1.0, v100
	v_rcp_f32_e32 v91, v0
	v_add_f32_e32 v0, v102, v114
	v_mul_f32_e32 v0, 0xbfb8aa3b, v0
	v_exp_f32_e32 v0, v0
	v_mul_f32_e32 v93, 0xbfb8aa3b, v93
	v_exp_f32_e32 v101, v93
	v_cvt_f32_f16_sdwa v93, v110 dst_sel:DWORD dst_unused:UNUSED_PAD src0_sel:WORD_1
	v_add_f32_e32 v0, 1.0, v0
	v_rcp_f32_e32 v100, v0
	v_add_f32_e32 v0, 1.0, v101
	v_rcp_f32_e32 v101, v0
	v_cvt_f32_f16_e32 v102, v111
	v_cvt_f32_f16_sdwa v103, v111 dst_sel:DWORD dst_unused:UNUSED_PAD src0_sel:WORD_1
	v_pk_mul_f32 v[90:91], v[90:91], v[92:93]
	ds_read_b128 v[74:77], v107 offset:17536
	v_cvt_pk_f16_f32 v90, v90, v91
	v_pk_mul_f32 v[92:93], v[100:101], v[102:103]
	v_mfma_f32_16x16x32_f16 v[18:21], v[94:97], v[18:21], v[144:147]
	v_cvt_pk_f16_f32 v91, v92, v93
	global_store_dwordx2 v[98:99], v[90:91], off offset:96
	global_load_dwordx4 v[90:93], v106, s[4:5] offset:256
	v_mfma_f32_16x16x32_f16 v[94:97], v[176:179], v[10:13], v[180:183]
	ds_read_b128 v[100:103], v107 offset:17600
	ds_read_b128 v[110:113], v107 offset:21888
	s_waitcnt lgkmcnt(2)
	v_mfma_f32_16x16x32_f16 v[74:77], v[74:77], v[6:9], v[94:97]
	s_waitcnt lgkmcnt(1)
; __device__ __forceinline__ float sigmoidf_(float x) { return __builtin_amdgcn_rcpf(1.0f + __expf(-x)); }
; __device__ __forceinline__ void s5d_wg(const int wvs, const Params& p, LAS unsigned char* lds, int layer, int task) {
;     ...
; #pragma unroll
;   for (int nt = 0; nt < 16; ++nt) { const int n4 = nt * 16 + fq * 4; const h4 zz = *(const h4*)(P + tok * PP + PC_S5 + n4); const f32x4 b4 = *(const f32x4*)(gb + n4); h4 o;
; #pragma unroll
;     for (int r = 0; r < 4; ++r) o[r] = (hf)((float)zz[r] * sigmoidf_(acc[nt][r] + b4[r]));
;     *(h4*)(Y + tok * DM + n4) = o; }
	v_mfma_f32_16x16x32_f16 v[74:77], v[100:103], v[2:5], v[74:77]
	s_waitcnt vmcnt(2)
	s_nop 0
	v_cvt_f32_f16_e32 v94, v104
	v_cvt_f32_f16_sdwa v95, v104 dst_sel:DWORD dst_unused:UNUSED_PAD src0_sel:WORD_1
	v_cvt_f32_f16_e32 v96, v105
	v_cvt_f32_f16_sdwa v97, v105 dst_sel:DWORD dst_unused:UNUSED_PAD src0_sel:WORD_1
	v_mfma_f32_16x16x32_f16 v[62:65], v[62:65], v[10:13], v[66:69]
	s_nop 2
	global_load_dwordx2 v[68:69], v[108:109], off offset:160
	global_load_dwordx2 v[114:115], v[108:109], off offset:192
	global_load_dwordx2 v[66:67], v[108:109], off offset:224
	s_waitcnt vmcnt(3)
	v_add_f32_e32 v0, v74, v90
	v_add_f32_e32 v74, v75, v91
	v_add_f32_e32 v75, v76, v92
	v_add_f32_e32 v76, v77, v93
	v_mul_f32_e32 v0, 0xbfb8aa3b, v0
	v_mul_f32_e32 v74, 0xbfb8aa3b, v74
	v_mul_f32_e32 v75, 0xbfb8aa3b, v75
	v_mul_f32_e32 v76, 0xbfb8aa3b, v76
	v_exp_f32_e32 v0, v0
	v_exp_f32_e32 v74, v74
	v_exp_f32_e32 v75, v75
	v_exp_f32_e32 v76, v76
	v_add_f32_e32 v0, 1.0, v0
	v_add_f32_e32 v74, 1.0, v74
	v_add_f32_e32 v75, 1.0, v75
	v_add_f32_e32 v76, 1.0, v76
	v_rcp_f32_e32 v90, v0
	v_rcp_f32_e32 v91, v74
	v_rcp_f32_e32 v92, v75
	v_rcp_f32_e32 v93, v76
	ds_read_b128 v[74:77], v107 offset:21952
	v_pk_mul_f32 v[90:91], v[90:91], v[94:95]
	v_mfma_f32_16x16x32_f16 v[82:85], v[184:187], v[10:13], v[188:191]
	v_mul_f32_e64 v92, v92, v96
	v_mul_f32_e64 v93, v93, v97
	v_cvt_pk_f16_f32 v90, v90, v91
	v_cvt_pk_f16_f32 v91, v92, v93
	global_store_dwordx2 v[98:99], v[90:91], off offset:128
	global_load_dwordx4 v[90:93], v106, s[4:5] offset:320
	s_waitcnt lgkmcnt(1)
	v_mfma_f32_16x16x32_f16 v[82:85], v[110:113], v[6:9], v[82:85]
	ds_read_b128 v[94:97], v107 offset:26240
	v_mfma_f32_16x16x32_f16 v[46:49], v[46:49], v[10:13], v[50:53]
	s_nop 2
	ds_read_b128 v[50:53], v107 offset:34944
	s_waitcnt lgkmcnt(2)
	v_mfma_f32_16x16x32_f16 v[74:77], v[74:77], v[2:5], v[82:85]
	s_waitcnt vmcnt(4)
	s_nop 1
	v_cvt_f32_f16_e32 v82, v68
	v_cvt_f32_f16_sdwa v83, v68 dst_sel:DWORD dst_unused:UNUSED_PAD src0_sel:WORD_1
	v_cvt_f32_f16_e32 v68, v69
	v_cvt_f32_f16_sdwa v69, v69 dst_sel:DWORD dst_unused:UNUSED_PAD src0_sel:WORD_1
	v_mfma_f32_16x16x32_f16 v[78:81], v[194:197], v[10:13], v[224:227]
	s_waitcnt vmcnt(0)
	v_add_f32_e32 v0, v74, v90
	v_add_f32_e32 v74, v75, v91
	v_add_f32_e32 v75, v76, v92
	v_add_f32_e32 v76, v77, v93
	v_mul_f32_e32 v0, 0xbfb8aa3b, v0
	v_mul_f32_e32 v74, 0xbfb8aa3b, v74
	v_mul_f32_e32 v75, 0xbfb8aa3b, v75
	v_mul_f32_e32 v76, 0xbfb8aa3b, v76
	v_exp_f32_e32 v0, v0
	v_exp_f32_e32 v74, v74
	v_exp_f32_e32 v75, v75
	v_exp_f32_e32 v76, v76
	v_add_f32_e32 v0, 1.0, v0
	v_add_f32_e32 v74, 1.0, v74
	v_add_f32_e32 v75, 1.0, v75
	v_add_f32_e32 v76, 1.0, v76
	v_rcp_f32_e32 v84, v0
	v_rcp_f32_e32 v85, v74
	v_rcp_f32_e32 v90, v75
	v_rcp_f32_e32 v91, v76
	ds_read_b128 v[74:77], v107 offset:26304
	v_pk_mul_f32 v[82:83], v[84:85], v[82:83]
	s_waitcnt lgkmcnt(2)
	v_mfma_f32_16x16x32_f16 v[78:81], v[94:97], v[6:9], v[78:81]
	v_mul_f32_e64 v68, v90, v68
	v_mul_f32_e64 v69, v91, v69
	v_cvt_pk_f16_f32 v82, v82, v83
	v_cvt_pk_f16_f32 v83, v68, v69
	global_store_dwordx2 v[98:99], v[82:83], off offset:160
	global_load_dwordx4 v[82:85], v106, s[4:5] offset:384
	s_waitcnt lgkmcnt(0)
	v_mfma_f32_16x16x32_f16 v[74:77], v[74:77], v[2:5], v[78:81]
	v_cvt_f32_f16_e32 v68, v114
	v_cvt_f32_f16_sdwa v69, v114 dst_sel:DWORD dst_unused:UNUSED_PAD src0_sel:WORD_1
	v_cvt_f32_f16_e32 v94, v115
	v_cvt_f32_f16_sdwa v95, v115 dst_sel:DWORD dst_unused:UNUSED_PAD src0_sel:WORD_1
	ds_read_b128 v[90:93], v107 offset:30592
	v_mfma_f32_16x16x32_f16 v[54:57], v[54:57], v[10:13], v[58:61]
	s_waitcnt vmcnt(0)
	s_nop 0
	v_add_f32_e32 v0, v74, v82
	v_add_f32_e32 v74, v75, v83
	v_add_f32_e32 v75, v76, v84
	v_add_f32_e32 v76, v77, v85
	v_mul_f32_e32 v0, 0xbfb8aa3b, v0
	v_mul_f32_e32 v74, 0xbfb8aa3b, v74
	v_mul_f32_e32 v75, 0xbfb8aa3b, v75
	v_mul_f32_e32 v76, 0xbfb8aa3b, v76
	v_exp_f32_e32 v0, v0
	v_exp_f32_e32 v74, v74
	v_exp_f32_e32 v75, v75
	v_exp_f32_e32 v76, v76
	v_add_f32_e32 v0, 1.0, v0
	v_add_f32_e32 v74, 1.0, v74
	v_add_f32_e32 v75, 1.0, v75
	v_add_f32_e32 v76, 1.0, v76
	v_rcp_f32_e32 v82, v0
	v_rcp_f32_e32 v83, v74
	v_rcp_f32_e32 v84, v75
	v_rcp_f32_e32 v85, v76
	ds_read_b128 v[74:77], v107 offset:30656
	v_pk_mul_f32 v[68:69], v[82:83], v[68:69]
	s_waitcnt lgkmcnt(1)
	v_mfma_f32_16x16x32_f16 v[78:81], v[90:93], v[6:9], v[86:89]
	v_mul_f32_e64 v82, v84, v94
	v_mul_f32_e64 v83, v85, v95
	v_cvt_pk_f16_f32 v68, v68, v69
	v_cvt_pk_f16_f32 v69, v82, v83
	global_store_dwordx2 v[98:99], v[68:69], off offset:192
	global_load_dwordx4 v[82:85], v106, s[4:5] offset:448
	s_waitcnt lgkmcnt(0)
	v_mfma_f32_16x16x32_f16 v[74:77], v[74:77], v[2:5], v[78:81]
	v_cvt_f32_f16_e32 v68, v66
	v_cvt_f32_f16_sdwa v69, v66 dst_sel:DWORD dst_unused:UNUSED_PAD src0_sel:WORD_1
	v_cvt_f32_f16_e32 v66, v67
	v_cvt_f32_f16_sdwa v67, v67 dst_sel:DWORD dst_unused:UNUSED_PAD src0_sel:WORD_1
	v_mfma_f32_16x16x32_f16 v[50:53], v[50:53], v[6:9], v[70:73]
	s_waitcnt vmcnt(0)
	s_nop 1
	v_add_f32_e32 v0, v74, v82
	v_add_f32_e32 v74, v75, v83
	v_add_f32_e32 v75, v76, v84
	v_add_f32_e32 v76, v77, v85
	v_mul_f32_e32 v0, 0xbfb8aa3b, v0
	v_mul_f32_e32 v74, 0xbfb8aa3b, v74
	v_mul_f32_e32 v75, 0xbfb8aa3b, v75
	v_mul_f32_e32 v76, 0xbfb8aa3b, v76
	v_exp_f32_e32 v0, v0
	v_exp_f32_e32 v74, v74
	v_exp_f32_e32 v75, v75
	v_exp_f32_e32 v76, v76
	v_add_f32_e32 v0, 1.0, v0
	v_add_f32_e32 v77, 1.0, v74
	v_add_f32_e32 v78, 1.0, v75
	v_add_f32_e32 v79, 1.0, v76
	v_rcp_f32_e32 v74, v0
	v_rcp_f32_e32 v75, v77
	v_rcp_f32_e32 v76, v78
	v_rcp_f32_e32 v77, v79
	global_load_dwordx2 v[78:79], v[108:109], off offset:256
	v_pk_mul_f32 v[58:59], v[74:75], v[68:69]
	v_mfma_f32_16x16x32_f16 v[38:41], v[38:41], v[10:13], v[42:45]
	v_mul_f32_e64 v60, v76, v66
	v_mul_f32_e64 v61, v77, v67
	v_cvt_pk_f16_f32 v58, v58, v59
	v_cvt_pk_f16_f32 v59, v60, v61
	global_store_dwordx2 v[98:99], v[58:59], off offset:224
	global_load_dwordx4 v[58:61], v106, s[4:5] offset:512
	ds_read_b128 v[66:69], v107 offset:35008
	ds_read_b128 v[74:77], v107 offset:39296
	s_waitcnt lgkmcnt(1)
; __device__ __forceinline__ float sigmoidf_(float x) { return __builtin_amdgcn_rcpf(1.0f + __expf(-x)); }
; __device__ __forceinline__ void s5d_wg(const int wvs, const Params& p, LAS unsigned char* lds, int layer, int task) {
;     ...
; #pragma unroll
;   for (int nt = 0; nt < 16; ++nt) { const int n4 = nt * 16 + fq * 4; const h4 zz = *(const h4*)(P + tok * PP + PC_S5 + n4); const f32x4 b4 = *(const f32x4*)(gb + n4); h4 o;
; #pragma unroll
;     for (int r = 0; r < 4; ++r) o[r] = (hf)((float)zz[r] * sigmoidf_(acc[nt][r] + b4[r]));
;     *(h4*)(Y + tok * DM + n4) = o; }
	v_mfma_f32_16x16x32_f16 v[50:53], v[66:69], v[2:5], v[50:53]
	global_load_dwordx2 v[44:45], v[108:109], off offset:288
	global_load_dwordx2 v[70:71], v[108:109], off offset:320
	global_load_dwordx2 v[42:43], v[108:109], off offset:352
	s_waitcnt vmcnt(5)
	v_cvt_f32_f16_e32 v66, v78
	v_cvt_f32_f16_sdwa v67, v78 dst_sel:DWORD dst_unused:UNUSED_PAD src0_sel:WORD_1
	v_cvt_f32_f16_e32 v68, v79
	v_cvt_f32_f16_sdwa v69, v79 dst_sel:DWORD dst_unused:UNUSED_PAD src0_sel:WORD_1
	v_mfma_f32_16x16x32_f16 v[22:25], v[22:25], v[10:13], v[26:29]
	s_waitcnt vmcnt(3)
	v_add_f32_e32 v0, v50, v58
	v_add_f32_e32 v50, v51, v59
	v_add_f32_e32 v51, v52, v60
	v_add_f32_e32 v52, v53, v61
	v_mul_f32_e32 v0, 0xbfb8aa3b, v0
	v_mul_f32_e32 v50, 0xbfb8aa3b, v50
	v_mul_f32_e32 v51, 0xbfb8aa3b, v51
	v_mul_f32_e32 v52, 0xbfb8aa3b, v52
	v_exp_f32_e32 v0, v0
	v_exp_f32_e32 v50, v50
	v_exp_f32_e32 v51, v51
	v_exp_f32_e32 v52, v52
	v_add_f32_e32 v0, 1.0, v0
	v_add_f32_e32 v50, 1.0, v50
	v_add_f32_e32 v51, 1.0, v51
	v_add_f32_e32 v52, 1.0, v52
	v_rcp_f32_e32 v72, v0
	v_rcp_f32_e32 v73, v50
	v_rcp_f32_e32 v78, v51
	v_rcp_f32_e32 v79, v52
	s_waitcnt lgkmcnt(0)
	v_mfma_f32_16x16x32_f16 v[58:61], v[74:77], v[6:9], v[62:65]
	ds_read_b128 v[50:53], v107 offset:39360
	ds_read_b128 v[26:29], v107 offset:52352
	s_nop 0
	v_pk_mul_f32 v[62:63], v[72:73], v[66:67]
	v_pk_mul_f32 v[64:65], v[78:79], v[68:69]
	v_cvt_pk_f16_f32 v62, v62, v63
	v_cvt_pk_f16_f32 v63, v64, v65
	global_store_dwordx2 v[98:99], v[62:63], off offset:256
	global_load_dwordx4 v[62:65], v106, s[4:5] offset:576
	ds_read_b128 v[66:69], v107 offset:43648
	s_waitcnt lgkmcnt(2)
	v_mfma_f32_16x16x32_f16 v[50:53], v[50:53], v[2:5], v[58:61]
	s_waitcnt vmcnt(4)
	s_nop 1
	v_cvt_f32_f16_e32 v58, v44
	v_cvt_f32_f16_sdwa v59, v44 dst_sel:DWORD dst_unused:UNUSED_PAD src0_sel:WORD_1
	v_cvt_f32_f16_e32 v44, v45
	v_cvt_f32_f16_sdwa v45, v45 dst_sel:DWORD dst_unused:UNUSED_PAD src0_sel:WORD_1
	s_waitcnt lgkmcnt(0)
	v_mfma_f32_16x16x32_f16 v[54:57], v[66:69], v[6:9], v[54:57]
	s_waitcnt vmcnt(0)
	v_add_f32_e32 v0, v50, v62
	v_add_f32_e32 v50, v51, v63
	v_add_f32_e32 v51, v52, v64
	v_add_f32_e32 v52, v53, v65
	v_mul_f32_e32 v0, 0xbfb8aa3b, v0
	v_mul_f32_e32 v50, 0xbfb8aa3b, v50
	v_mul_f32_e32 v51, 0xbfb8aa3b, v51
	v_mul_f32_e32 v52, 0xbfb8aa3b, v52
	v_exp_f32_e32 v0, v0
	v_exp_f32_e32 v50, v50
	v_exp_f32_e32 v51, v51
	v_exp_f32_e32 v52, v52
	v_add_f32_e32 v0, 1.0, v0
	v_add_f32_e32 v50, 1.0, v50
	v_add_f32_e32 v51, 1.0, v51
	v_add_f32_e32 v52, 1.0, v52
	v_rcp_f32_e32 v60, v0
	v_rcp_f32_e32 v61, v50
	v_rcp_f32_e32 v62, v51
	v_rcp_f32_e32 v63, v52
	ds_read_b128 v[50:53], v107 offset:43712
	v_pk_mul_f32 v[58:59], v[60:61], v[58:59]
	v_mfma_f32_16x16x32_f16 v[30:33], v[30:33], v[10:13], v[34:37]
	v_mul_f32_e64 v44, v62, v44
	v_mul_f32_e64 v45, v63, v45
	v_cvt_pk_f16_f32 v58, v58, v59
	v_cvt_pk_f16_f32 v59, v44, v45
	global_store_dwordx2 v[98:99], v[58:59], off offset:288
	global_load_dwordx4 v[58:61], v106, s[4:5] offset:640
	ds_read_b128 v[62:65], v107 offset:48000
	s_waitcnt lgkmcnt(1)
	v_mfma_f32_16x16x32_f16 v[50:53], v[50:53], v[2:5], v[54:57]
	s_nop 2
	v_cvt_f32_f16_e32 v54, v70
	v_cvt_f32_f16_sdwa v55, v70 dst_sel:DWORD dst_unused:UNUSED_PAD src0_sel:WORD_1
	v_cvt_f32_f16_e32 v56, v71
	v_cvt_f32_f16_sdwa v57, v71 dst_sel:DWORD dst_unused:UNUSED_PAD src0_sel:WORD_1
	v_mfma_f32_16x16x32_f16 v[10:13], v[14:17], v[10:13], v[18:21]
	s_waitcnt vmcnt(0)
	v_add_f32_e32 v0, v50, v58
	v_add_f32_e32 v44, v51, v59
	v_add_f32_e32 v45, v52, v60
	v_add_f32_e32 v50, v53, v61
	v_mul_f32_e32 v0, 0xbfb8aa3b, v0
	v_mul_f32_e32 v44, 0xbfb8aa3b, v44
	v_mul_f32_e32 v45, 0xbfb8aa3b, v45
	v_mul_f32_e32 v50, 0xbfb8aa3b, v50
	v_exp_f32_e32 v0, v0
	v_exp_f32_e32 v44, v44
	v_exp_f32_e32 v45, v45
	v_exp_f32_e32 v50, v50
	v_add_f32_e32 v0, 1.0, v0
	v_add_f32_e32 v44, 1.0, v44
	v_add_f32_e32 v45, 1.0, v45
	v_add_f32_e32 v50, 1.0, v50
	v_rcp_f32_e32 v58, v0
	v_rcp_f32_e32 v59, v44
	v_rcp_f32_e32 v60, v45
	v_rcp_f32_e32 v61, v50
	s_waitcnt lgkmcnt(0)
	v_mfma_f32_16x16x32_f16 v[44:47], v[62:65], v[6:9], v[46:49]
	ds_read_b128 v[50:53], v107 offset:48064
	s_nop 1
	v_pk_mul_f32 v[48:49], v[58:59], v[54:55]
	v_pk_mul_f32 v[54:55], v[60:61], v[56:57]
	v_cvt_pk_f16_f32 v48, v48, v49
	v_cvt_pk_f16_f32 v49, v54, v55
	global_store_dwordx2 v[98:99], v[48:49], off offset:320
	global_load_dwordx4 v[54:57], v106, s[4:5] offset:704
	s_waitcnt lgkmcnt(0)
	v_mfma_f32_16x16x32_f16 v[44:47], v[50:53], v[2:5], v[44:47]
	v_cvt_f32_f16_e32 v48, v42
	v_cvt_f32_f16_sdwa v49, v42 dst_sel:DWORD dst_unused:UNUSED_PAD src0_sel:WORD_1
	v_cvt_f32_f16_e32 v42, v43
	v_cvt_f32_f16_sdwa v43, v43 dst_sel:DWORD dst_unused:UNUSED_PAD src0_sel:WORD_1
	v_mfma_f32_16x16x32_f16 v[26:29], v[26:29], v[6:9], v[38:41]
	s_waitcnt vmcnt(0)
	s_nop 1
	v_add_f32_e32 v0, v44, v54
	v_add_f32_e32 v44, v45, v55
	v_add_f32_e32 v45, v46, v56
	v_add_f32_e32 v46, v47, v57
	v_mul_f32_e32 v0, 0xbfb8aa3b, v0
	v_mul_f32_e32 v44, 0xbfb8aa3b, v44
	v_mul_f32_e32 v45, 0xbfb8aa3b, v45
	v_mul_f32_e32 v46, 0xbfb8aa3b, v46
	v_exp_f32_e32 v0, v0
	v_exp_f32_e32 v44, v44
	v_exp_f32_e32 v45, v45
	v_exp_f32_e32 v46, v46
	v_add_f32_e32 v0, 1.0, v0
	v_add_f32_e32 v47, 1.0, v44
	v_add_f32_e32 v50, 1.0, v45
	v_add_f32_e32 v51, 1.0, v46
	v_rcp_f32_e32 v44, v0
	v_rcp_f32_e32 v45, v47
	v_rcp_f32_e32 v46, v50
	v_rcp_f32_e32 v47, v51
	global_load_dwordx2 v[50:51], v[108:109], off offset:384
	v_pk_mul_f32 v[34:35], v[44:45], v[48:49]
	v_pk_mul_f32 v[36:37], v[46:47], v[42:43]
	v_cvt_pk_f16_f32 v34, v34, v35
	v_cvt_pk_f16_f32 v35, v36, v37
	global_store_dwordx2 v[98:99], v[34:35], off offset:352
	global_load_dwordx4 v[34:37], v106, s[4:5] offset:768
	ds_read_b128 v[16:19], v107 offset:52416
	ds_read_b128 v[42:45], v107 offset:56704
	s_waitcnt lgkmcnt(1)
; __device__ __forceinline__ float sigmoidf_(float x) { return __builtin_amdgcn_rcpf(1.0f + __expf(-x)); }
; __device__ __forceinline__ void s5d_wg(const int wvs, const Params& p, LAS unsigned char* lds, int layer, int task) {
;     ...
; #pragma unroll
;   for (int nt = 0; nt < 16; ++nt) { const int n4 = nt * 16 + fq * 4; const h4 zz = *(const h4*)(P + tok * PP + PC_S5 + n4); const f32x4 b4 = *(const f32x4*)(gb + n4); h4 o;
; #pragma unroll
;     for (int r = 0; r < 4; ++r) o[r] = (hf)((float)zz[r] * sigmoidf_(acc[nt][r] + b4[r]));
;     *(h4*)(Y + tok * DM + n4) = o; }
	v_mfma_f32_16x16x32_f16 v[16:19], v[16:19], v[2:5], v[26:29]
	global_load_dwordx2 v[20:21], v[108:109], off offset:416
	global_load_dwordx2 v[38:39], v[108:109], off offset:448
	global_load_dwordx2 v[14:15], v[108:109], off offset:480
	s_waitcnt vmcnt(5)
	v_cvt_f32_f16_e32 v40, v50
	v_cvt_f32_f16_sdwa v41, v50 dst_sel:DWORD dst_unused:UNUSED_PAD src0_sel:WORD_1
	v_cvt_f32_f16_e32 v46, v51
	v_cvt_f32_f16_sdwa v47, v51 dst_sel:DWORD dst_unused:UNUSED_PAD src0_sel:WORD_1
	s_waitcnt lgkmcnt(0)
	v_mfma_f32_16x16x32_f16 v[26:29], v[42:45], v[6:9], v[30:33]
	s_waitcnt vmcnt(3)
	v_add_f32_e32 v0, v16, v34
	v_add_f32_e32 v16, v17, v35
	v_add_f32_e32 v17, v18, v36
	v_add_f32_e32 v18, v19, v37
	v_mul_f32_e32 v0, 0xbfb8aa3b, v0
	v_mul_f32_e32 v16, 0xbfb8aa3b, v16
	v_mul_f32_e32 v17, 0xbfb8aa3b, v17
	v_mul_f32_e32 v18, 0xbfb8aa3b, v18
	v_exp_f32_e32 v0, v0
	v_exp_f32_e32 v16, v16
	v_exp_f32_e32 v17, v17
	v_exp_f32_e32 v18, v18
	v_add_f32_e32 v0, 1.0, v0
	v_add_f32_e32 v16, 1.0, v16
	v_add_f32_e32 v17, 1.0, v17
	v_add_f32_e32 v18, 1.0, v18
	v_rcp_f32_e32 v34, v0
	v_rcp_f32_e32 v35, v16
	v_rcp_f32_e32 v36, v17
	v_rcp_f32_e32 v37, v18
	ds_read_b128 v[16:19], v107 offset:56768
	v_pk_mul_f32 v[30:31], v[34:35], v[40:41]
	v_pk_mul_f32 v[32:33], v[36:37], v[46:47]
	v_cvt_pk_f16_f32 v30, v30, v31
	v_cvt_pk_f16_f32 v31, v32, v33
	global_store_dwordx2 v[98:99], v[30:31], off offset:384
	global_load_dwordx4 v[30:33], v106, s[4:5] offset:832
	ds_read_b128 v[34:37], v107 offset:61056
	s_waitcnt lgkmcnt(1)
	v_mfma_f32_16x16x32_f16 v[16:19], v[16:19], v[2:5], v[26:29]
	s_waitcnt vmcnt(4)
	s_nop 1
	v_cvt_f32_f16_e32 v26, v20
	v_cvt_f32_f16_sdwa v27, v20 dst_sel:DWORD dst_unused:UNUSED_PAD src0_sel:WORD_1
	v_cvt_f32_f16_e32 v28, v21
	v_cvt_f32_f16_sdwa v29, v21 dst_sel:DWORD dst_unused:UNUSED_PAD src0_sel:WORD_1
	s_waitcnt lgkmcnt(0)
	v_mfma_f32_16x16x32_f16 v[20:23], v[34:37], v[6:9], v[22:25]
	s_waitcnt vmcnt(0)
	v_add_f32_e32 v0, v16, v30
	v_add_f32_e32 v16, v17, v31
	v_add_f32_e32 v17, v18, v32
	v_add_f32_e32 v18, v19, v33
	v_mul_f32_e32 v0, 0xbfb8aa3b, v0
	v_mul_f32_e32 v16, 0xbfb8aa3b, v16
	v_mul_f32_e32 v17, 0xbfb8aa3b, v17
	v_mul_f32_e32 v18, 0xbfb8aa3b, v18
	v_exp_f32_e32 v0, v0
	v_exp_f32_e32 v16, v16
	v_exp_f32_e32 v17, v17
	v_exp_f32_e32 v18, v18
	v_add_f32_e32 v0, 1.0, v0
	v_add_f32_e32 v16, 1.0, v16
	v_add_f32_e32 v17, 1.0, v17
	v_add_f32_e32 v18, 1.0, v18
	v_rcp_f32_e32 v30, v0
	v_rcp_f32_e32 v31, v16
	v_rcp_f32_e32 v32, v17
	v_rcp_f32_e32 v33, v18
	ds_read_b128 v[16:19], v107 offset:61120
	v_pk_mul_f32 v[24:25], v[30:31], v[26:27]
	v_pk_mul_f32 v[26:27], v[32:33], v[28:29]
	v_cvt_pk_f16_f32 v24, v24, v25
	v_cvt_pk_f16_f32 v25, v26, v27
	global_store_dwordx2 v[98:99], v[24:25], off offset:416
	global_load_dwordx4 v[24:27], v106, s[4:5] offset:896
	ds_read_b128 v[28:31], v107 offset:65408
	s_waitcnt lgkmcnt(1)
	v_mfma_f32_16x16x32_f16 v[16:19], v[16:19], v[2:5], v[20:23]
	s_nop 2
	v_cvt_f32_f16_e32 v20, v38
	v_cvt_f32_f16_sdwa v21, v38 dst_sel:DWORD dst_unused:UNUSED_PAD src0_sel:WORD_1
	v_cvt_f32_f16_e32 v22, v39
	v_cvt_f32_f16_sdwa v23, v39 dst_sel:DWORD dst_unused:UNUSED_PAD src0_sel:WORD_1
	s_waitcnt lgkmcnt(0)
	v_mfma_f32_16x16x32_f16 v[6:9], v[28:31], v[6:9], v[10:13]
	s_waitcnt vmcnt(0)
	v_add_f32_e32 v0, v16, v24
	v_add_f32_e32 v16, v17, v25
	v_add_f32_e32 v17, v18, v26
	v_add_f32_e32 v18, v19, v27
	v_mul_f32_e32 v0, 0xbfb8aa3b, v0
	v_mul_f32_e32 v16, 0xbfb8aa3b, v16
	v_mul_f32_e32 v17, 0xbfb8aa3b, v17
	v_mul_f32_e32 v18, 0xbfb8aa3b, v18
	v_exp_f32_e32 v0, v0
	v_exp_f32_e32 v16, v16
	v_exp_f32_e32 v17, v17
	v_exp_f32_e32 v18, v18
	v_add_f32_e32 v0, 1.0, v0
	v_add_f32_e32 v16, 1.0, v16
	v_add_f32_e32 v17, 1.0, v17
	v_add_f32_e32 v18, 1.0, v18
	v_rcp_f32_e32 v24, v0
	v_rcp_f32_e32 v25, v16
	v_rcp_f32_e32 v26, v17
	v_rcp_f32_e32 v27, v18
	ds_read_b128 v[16:19], v107 offset:65472
	v_pk_mul_f32 v[10:11], v[24:25], v[20:21]
	s_waitcnt lgkmcnt(0)
	v_mfma_f32_16x16x32_f16 v[2:5], v[16:19], v[2:5], v[6:9]
	v_mul_f32_e64 v12, v26, v22
	v_mul_f32_e64 v13, v27, v23
	v_cvt_pk_f16_f32 v10, v10, v11
	v_cvt_pk_f16_f32 v11, v12, v13
	global_store_dwordx2 v[98:99], v[10:11], off offset:448
	global_load_dwordx4 v[10:13], v106, s[4:5] offset:960
	v_cvt_f32_f16_e32 v6, v14
	v_cvt_f32_f16_sdwa v7, v14 dst_sel:DWORD dst_unused:UNUSED_PAD src0_sel:WORD_1
	v_cvt_f32_f16_e32 v8, v15
	v_cvt_f32_f16_sdwa v9, v15 dst_sel:DWORD dst_unused:UNUSED_PAD src0_sel:WORD_1
	s_waitcnt vmcnt(0)
	v_add_f32_e32 v0, v2, v10
	v_add_f32_e32 v2, v3, v11
	v_add_f32_e32 v3, v4, v12
	v_add_f32_e32 v4, v5, v13
	v_mul_f32_e32 v0, 0xbfb8aa3b, v0
	v_mul_f32_e32 v2, 0xbfb8aa3b, v2
	v_mul_f32_e32 v3, 0xbfb8aa3b, v3
	v_mul_f32_e32 v4, 0xbfb8aa3b, v4
	v_exp_f32_e32 v0, v0
	v_exp_f32_e32 v2, v2
	v_exp_f32_e32 v3, v3
	v_exp_f32_e32 v4, v4
	v_add_f32_e32 v0, 1.0, v0
	v_add_f32_e32 v5, 1.0, v2
	v_add_f32_e32 v10, 1.0, v3
	v_add_f32_e32 v11, 1.0, v4
	v_rcp_f32_e32 v2, v0
	v_rcp_f32_e32 v3, v5
	v_rcp_f32_e32 v4, v10
	v_rcp_f32_e32 v5, v11
	v_pk_mul_f32 v[2:3], v[2:3], v[6:7]
	s_nop 0
	v_cvt_pk_f16_f32 v2, v2, v3
	v_pk_mul_f32 v[4:5], v[4:5], v[8:9]
	s_nop 0
	v_cvt_pk_f16_f32 v3, v4, v5
	global_store_dwordx2 v[98:99], v[2:3], off offset:480
